# Minv pre-pass: inverse rows transposed through LDS and written with one 16-byte store per lane instead of 16 dword stores
# speedup vs baseline: 1.0079x; 1.0079x over previous
.Lmv_item:
	s_cmp_ge_u32 s2, 0x2010
	s_cbranch_scc1 .Lmv_done
	s_mul_hi_u32 s13, s2, 0x7fc020
	s_mul_i32 s14, s13, 0x201
	s_sub_u32 s14, s2, s14
	s_lshr_b32 s15, s13, 2
	s_and_b32 s16, s13, 3
	s_mul_i32 s17, s15, 0x2080
	s_lshl_b32 s18, s14, 4
	s_add_i32 s17, s17, s18
	s_add_i32 s17, s17, 0x70
	s_mul_i32 s18, s17, 0xc00
	s_lshl_b32 s19, s16, 8
	s_add_i32 s18, s18, s19
	s_add_i32 s18, s18, 0x400
	v_add_u32_e32 v156, s18, v153
	s_lshl_b32 s19, s17, 5
	s_lshl_b32 s20, s16, 2
	s_add_i32 s19, s19, s20
	s_add_i32 s19, s19, 0x19c8c010
	v_add_u32_e32 v157, s19, v154
	global_load_dwordx4 v[64:67], v156, s[4:5]
	global_load_dwordx4 v[68:71], v156, s[4:5] offset:16
	global_load_dwordx4 v[72:75], v156, s[4:5] offset:32
	global_load_dwordx4 v[76:79], v156, s[4:5] offset:48
	global_load_dword v158, v157, s[6:7]
	v_add_u32_e32 v156, 0xfffffc00, v156
	global_load_dwordx4 v[226:229], v156, s[4:5]
	global_load_dwordx4 v[230:233], v156, s[4:5] offset:16
	global_load_dwordx4 v[234:237], v156, s[4:5] offset:32
	global_load_dwordx4 v[238:241], v156, s[4:5] offset:48
	s_waitcnt vmcnt(4)
	v_lshlrev_b32_e32 v32, 16, v64
	v_and_b32_e32 v33, 0xffff0000, v64
	v_lshlrev_b32_e32 v34, 16, v65
	v_and_b32_e32 v35, 0xffff0000, v65
	v_lshlrev_b32_e32 v36, 16, v66
	v_and_b32_e32 v37, 0xffff0000, v66
	v_lshlrev_b32_e32 v38, 16, v67
	v_and_b32_e32 v39, 0xffff0000, v67
	v_lshlrev_b32_e32 v40, 16, v68
	v_and_b32_e32 v41, 0xffff0000, v68
	v_lshlrev_b32_e32 v42, 16, v69
	v_and_b32_e32 v43, 0xffff0000, v69
	v_lshlrev_b32_e32 v44, 16, v70
	v_and_b32_e32 v45, 0xffff0000, v70
	v_lshlrev_b32_e32 v46, 16, v71
	v_and_b32_e32 v47, 0xffff0000, v71
	v_lshlrev_b32_e32 v48, 16, v72
	v_and_b32_e32 v49, 0xffff0000, v72
	v_lshlrev_b32_e32 v50, 16, v73
	v_and_b32_e32 v51, 0xffff0000, v73
	v_lshlrev_b32_e32 v52, 16, v74
	v_and_b32_e32 v53, 0xffff0000, v74
	v_lshlrev_b32_e32 v54, 16, v75
	v_and_b32_e32 v55, 0xffff0000, v75
	v_lshlrev_b32_e32 v56, 16, v76
	v_and_b32_e32 v57, 0xffff0000, v76
	v_lshlrev_b32_e32 v58, 16, v77
	v_and_b32_e32 v59, 0xffff0000, v77
	v_lshlrev_b32_e32 v60, 16, v78
	v_and_b32_e32 v61, 0xffff0000, v78
	v_lshlrev_b32_e32 v62, 16, v79
	v_and_b32_e32 v63, 0xffff0000, v79
	v_lshl_add_u32 v156, v152, 2, s12
	ds_write_b32 v156, v158 offset:1024
	v_mfma_f32_16x16x4_f32 v[80:83], v32, v32, 0
	v_mfma_f32_16x16x4_f32 v[84:87], v33, v33, 0
	v_mfma_f32_16x16x4_f32 v[80:83], v34, v34, v[80:83]
	v_mfma_f32_16x16x4_f32 v[84:87], v35, v35, v[84:87]
	v_mfma_f32_16x16x4_f32 v[80:83], v36, v36, v[80:83]
	v_mfma_f32_16x16x4_f32 v[84:87], v37, v37, v[84:87]
	v_mfma_f32_16x16x4_f32 v[80:83], v38, v38, v[80:83]
	v_mfma_f32_16x16x4_f32 v[84:87], v39, v39, v[84:87]
	v_mfma_f32_16x16x4_f32 v[80:83], v40, v40, v[80:83]
	v_mfma_f32_16x16x4_f32 v[84:87], v41, v41, v[84:87]
	v_mfma_f32_16x16x4_f32 v[80:83], v42, v42, v[80:83]
	v_mfma_f32_16x16x4_f32 v[84:87], v43, v43, v[84:87]
	v_mfma_f32_16x16x4_f32 v[80:83], v44, v44, v[80:83]
	v_mfma_f32_16x16x4_f32 v[84:87], v45, v45, v[84:87]
	v_mfma_f32_16x16x4_f32 v[80:83], v46, v46, v[80:83]
	v_mfma_f32_16x16x4_f32 v[84:87], v47, v47, v[84:87]
	v_mfma_f32_16x16x4_f32 v[80:83], v48, v48, v[80:83]
	v_mfma_f32_16x16x4_f32 v[84:87], v49, v49, v[84:87]
	v_mfma_f32_16x16x4_f32 v[80:83], v50, v50, v[80:83]
	v_mfma_f32_16x16x4_f32 v[84:87], v51, v51, v[84:87]
	v_mfma_f32_16x16x4_f32 v[80:83], v52, v52, v[80:83]
	v_mfma_f32_16x16x4_f32 v[84:87], v53, v53, v[84:87]
	v_mfma_f32_16x16x4_f32 v[80:83], v54, v54, v[80:83]
	v_mfma_f32_16x16x4_f32 v[84:87], v55, v55, v[84:87]
	v_mfma_f32_16x16x4_f32 v[80:83], v56, v56, v[80:83]
	v_mfma_f32_16x16x4_f32 v[84:87], v57, v57, v[84:87]
	v_mfma_f32_16x16x4_f32 v[80:83], v58, v58, v[80:83]
	v_mfma_f32_16x16x4_f32 v[84:87], v59, v59, v[84:87]
	v_mfma_f32_16x16x4_f32 v[80:83], v60, v60, v[80:83]
	v_mfma_f32_16x16x4_f32 v[84:87], v61, v61, v[84:87]
	v_mfma_f32_16x16x4_f32 v[80:83], v62, v62, v[80:83]
	v_mfma_f32_16x16x4_f32 v[84:87], v63, v63, v[84:87]
	s_waitcnt vmcnt(0)
	v_lshlrev_b32_e32 v166, 16, v226
	v_and_b32_e32 v167, 0xffff0000, v226
	v_lshlrev_b32_e32 v168, 16, v227
	v_and_b32_e32 v169, 0xffff0000, v227
	v_lshlrev_b32_e32 v170, 16, v228
	v_and_b32_e32 v171, 0xffff0000, v228
	v_lshlrev_b32_e32 v172, 16, v229
	v_and_b32_e32 v173, 0xffff0000, v229
	v_lshlrev_b32_e32 v174, 16, v230
	v_and_b32_e32 v175, 0xffff0000, v230
	v_lshlrev_b32_e32 v176, 16, v231
	v_and_b32_e32 v177, 0xffff0000, v231
	v_lshlrev_b32_e32 v178, 16, v232
	v_and_b32_e32 v179, 0xffff0000, v232
	v_lshlrev_b32_e32 v180, 16, v233
	v_and_b32_e32 v181, 0xffff0000, v233
	v_lshlrev_b32_e32 v182, 16, v234
	v_and_b32_e32 v183, 0xffff0000, v234
	v_lshlrev_b32_e32 v184, 16, v235
	v_and_b32_e32 v185, 0xffff0000, v235
	v_lshlrev_b32_e32 v186, 16, v236
	v_and_b32_e32 v187, 0xffff0000, v236
	v_lshlrev_b32_e32 v188, 16, v237
	v_and_b32_e32 v189, 0xffff0000, v237
	v_lshlrev_b32_e32 v190, 16, v238
	v_and_b32_e32 v191, 0xffff0000, v238
	v_lshlrev_b32_e32 v192, 16, v239
	v_and_b32_e32 v193, 0xffff0000, v239
	v_lshlrev_b32_e32 v194, 16, v240
	v_and_b32_e32 v195, 0xffff0000, v240
	v_lshlrev_b32_e32 v196, 16, v241
	v_and_b32_e32 v197, 0xffff0000, v241
	s_nop 0
	v_mfma_f32_16x16x4_f32 v[198:201], v166, v32, 0
	v_mfma_f32_16x16x4_f32 v[202:205], v167, v33, 0
	v_mfma_f32_16x16x4_f32 v[198:201], v168, v34, v[198:201]
	v_mfma_f32_16x16x4_f32 v[202:205], v169, v35, v[202:205]
	v_mfma_f32_16x16x4_f32 v[198:201], v170, v36, v[198:201]
	v_mfma_f32_16x16x4_f32 v[202:205], v171, v37, v[202:205]
	v_mfma_f32_16x16x4_f32 v[198:201], v172, v38, v[198:201]
	v_mfma_f32_16x16x4_f32 v[202:205], v173, v39, v[202:205]
	v_mfma_f32_16x16x4_f32 v[198:201], v174, v40, v[198:201]
	v_mfma_f32_16x16x4_f32 v[202:205], v175, v41, v[202:205]
	v_mfma_f32_16x16x4_f32 v[198:201], v176, v42, v[198:201]
	v_mfma_f32_16x16x4_f32 v[202:205], v177, v43, v[202:205]
	v_mfma_f32_16x16x4_f32 v[198:201], v178, v44, v[198:201]
	v_mfma_f32_16x16x4_f32 v[202:205], v179, v45, v[202:205]
	v_mfma_f32_16x16x4_f32 v[198:201], v180, v46, v[198:201]
	v_mfma_f32_16x16x4_f32 v[202:205], v181, v47, v[202:205]
	v_mfma_f32_16x16x4_f32 v[198:201], v182, v48, v[198:201]
	v_mfma_f32_16x16x4_f32 v[202:205], v183, v49, v[202:205]
	v_mfma_f32_16x16x4_f32 v[198:201], v184, v50, v[198:201]
	v_mfma_f32_16x16x4_f32 v[202:205], v185, v51, v[202:205]
	v_mfma_f32_16x16x4_f32 v[198:201], v186, v52, v[198:201]
	v_mfma_f32_16x16x4_f32 v[202:205], v187, v53, v[202:205]
	v_mfma_f32_16x16x4_f32 v[198:201], v188, v54, v[198:201]
	v_mfma_f32_16x16x4_f32 v[202:205], v189, v55, v[202:205]
	v_mfma_f32_16x16x4_f32 v[198:201], v190, v56, v[198:201]
	v_mfma_f32_16x16x4_f32 v[202:205], v191, v57, v[202:205]
	v_mfma_f32_16x16x4_f32 v[198:201], v192, v58, v[198:201]
	v_mfma_f32_16x16x4_f32 v[202:205], v193, v59, v[202:205]
	v_mfma_f32_16x16x4_f32 v[198:201], v194, v60, v[198:201]
	v_mfma_f32_16x16x4_f32 v[202:205], v195, v61, v[202:205]
	v_mfma_f32_16x16x4_f32 v[198:201], v196, v62, v[198:201]
	v_mfma_f32_16x16x4_f32 v[202:205], v197, v63, v[202:205]
	v_mov_b32_e32 v157, s12
	s_waitcnt lgkmcnt(0)
; __device__ __forceinline__ void gdn_item(const Params& p, int item, float* sm) {
;     ...
;       for (int t = 0; t < TC; t++) {
;         const float4 k0 = *(const float4*)(bk + t * 128 + sub * 4);
;         const float4 k1 = *(const float4*)(bk + t * 128 + 64 + sub * 4);
;         const float4 q0 = *(const float4*)(bq + t * 128 + sub * 4);
;         const float4 q1 = *(const float4*)(bq + t * 128 + 64 + sub * 4);
;         const float v = bv[t * 16 + cw];
;         const float g = bg[t], be = bg[TC + t];
;         const float qk = bo[TC * 16 + t];
;         float pa = k0.x * S[0] + k0.y * S[1];
;         float pb2 = k0.z * S[2] + k0.w * S[3];
;         float qa = q0.x * S[0] + q0.y * S[1];
;         float qb2 = q0.z * S[2] + q0.w * S[3];
;         pa += k1.x * S[4] + k1.y * S[5];
;         pb2 += k1.z * S[6] + k1.w * S[7];
;         qa += q1.x * S[4] + q1.y * S[5];
;         qb2 += q1.z * S[6] + q1.w * S[7];
;         const float ks = dpp_sum16(pa + pb2);
;         const float qs = dpp_sum16(qa + qb2);
;         const float coef = be * (v - g * ks);
;         const float oo = g * qs + coef * qk;
;         S[0] = g * S[0] + coef * k0.x; S[1] = g * S[1] + coef * k0.y; S[2] = g * S[2] + coef * k0.z; S[3] = g * S[3] + coef * k0.w;
;         S[4] = g * S[4] + coef * k1.x; S[5] = g * S[5] + coef * k1.y; S[6] = g * S[6] + coef * k1.z; S[7] = g * S[7] + coef * k1.w;
;         oreg[t] = oo * 0.08838834764831845f;
	ds_read_b128 v[88:91], v157 offset:1024
	ds_read_b128 v[92:95], v157 offset:1040
	ds_read_b128 v[96:99], v157 offset:1056
	ds_read_b128 v[100:103], v157 offset:1072
	v_add_f32_e32 v80, v80, v84
	v_add_f32_e32 v81, v81, v85
	v_add_f32_e32 v82, v82, v86
	v_add_f32_e32 v83, v83, v87
	ds_write_b128 v155, v[80:83]
	s_waitcnt lgkmcnt(0)
	ds_read_b128 v[136:139], v157 offset:64
	s_lshl_b32 s13, s2, 10
	s_add_i32 s18, s13, 0xac40000
	v_add_u32_e32 v156, s18, v242
	v_add_f32_e32 v198, v198, v202
	v_add_f32_e32 v199, v199, v203
	v_add_f32_e32 v200, v200, v204
	v_add_f32_e32 v201, v201, v205
	v_add_u32_e32 v159, 0, v160
	v_cmp_le_u32_e32 vcc, v152, v159
	s_nop 1
	v_cndmask_b32_e64 v198, 0, v198, vcc
	v_add_u32_e32 v159, 1, v160
	v_cmp_le_u32_e32 vcc, v152, v159
	s_nop 1
	v_cndmask_b32_e64 v199, 0, v199, vcc
	v_add_u32_e32 v159, 2, v160
	v_cmp_le_u32_e32 vcc, v152, v159
	s_nop 1
	v_cndmask_b32_e64 v200, 0, v200, vcc
	v_add_u32_e32 v159, 3, v160
	v_cmp_le_u32_e32 vcc, v152, v159
	s_nop 1
	v_cndmask_b32_e64 v201, 0, v201, vcc
	s_nop 0
	global_store_dword v156, v198, s[6:7]
	global_store_dword v156, v199, s[6:7] offset:64
	global_store_dword v156, v200, s[6:7] offset:128
	global_store_dword v156, v201, s[6:7] offset:192
	v_cmp_eq_u32_e32 vcc, 0, v152
	s_nop 1
	v_cndmask_b32_e64 v159, 0, 1.0, vcc
	v_mul_f32_e32 v104, v88, v159
	ds_read_b128 v[120:123], v157 offset:128
	v_cmp_eq_u32_e32 vcc, 1, v152
	s_waitcnt lgkmcnt(1)
	s_nop 0
	v_cndmask_b32_e64 v159, 0, 1.0, vcc
	v_fma_f32 v159, -v136, v104, v159
	v_mul_f32_e32 v105, v89, v159
	ds_read_b128 v[136:139], v157 offset:192
	v_cmp_eq_u32_e32 vcc, 2, v152
	s_waitcnt lgkmcnt(1)
	s_nop 0
	v_cndmask_b32_e64 v159, 0, 1.0, vcc
	v_fma_f32 v159, -v120, v104, v159
	v_fma_f32 v159, -v121, v105, v159
	v_mul_f32_e32 v106, v90, v159
	ds_read_b128 v[120:123], v157 offset:256
	v_cmp_eq_u32_e32 vcc, 3, v152
	s_waitcnt lgkmcnt(1)
	s_nop 0
	v_cndmask_b32_e64 v159, 0, 1.0, vcc
	v_fma_f32 v159, -v136, v104, v159
	v_fma_f32 v159, -v137, v105, v159
	v_fma_f32 v159, -v138, v106, v159
	v_mul_f32_e32 v107, v91, v159
	ds_read_b128 v[136:139], v157 offset:320
	ds_read_b128 v[140:143], v157 offset:336
	v_cmp_eq_u32_e32 vcc, 4, v152
	s_waitcnt lgkmcnt(2)
	s_nop 0
	v_cndmask_b32_e64 v159, 0, 1.0, vcc
	v_fma_f32 v159, -v120, v104, v159
	v_fma_f32 v159, -v121, v105, v159
	v_fma_f32 v159, -v122, v106, v159
	v_fma_f32 v159, -v123, v107, v159
	v_mul_f32_e32 v108, v92, v159
	ds_read_b128 v[120:123], v157 offset:384
	ds_read_b128 v[124:127], v157 offset:400
	v_cmp_eq_u32_e32 vcc, 5, v152
	s_waitcnt lgkmcnt(2)
	s_nop 0
	v_cndmask_b32_e64 v159, 0, 1.0, vcc
	v_fma_f32 v159, -v136, v104, v159
	v_fma_f32 v159, -v137, v105, v159
	v_fma_f32 v159, -v138, v106, v159
	v_fma_f32 v159, -v139, v107, v159
	v_fma_f32 v159, -v140, v108, v159
	v_mul_f32_e32 v109, v93, v159
	ds_read_b128 v[136:139], v157 offset:448
	ds_read_b128 v[140:143], v157 offset:464
	v_cmp_eq_u32_e32 vcc, 6, v152
	s_waitcnt lgkmcnt(2)
	s_nop 0
	v_cndmask_b32_e64 v159, 0, 1.0, vcc
	v_fma_f32 v159, -v120, v104, v159
	v_fma_f32 v159, -v121, v105, v159
	v_fma_f32 v159, -v122, v106, v159
	v_fma_f32 v159, -v123, v107, v159
	v_fma_f32 v159, -v124, v108, v159
	v_fma_f32 v159, -v125, v109, v159
	v_mul_f32_e32 v110, v94, v159
	ds_read_b128 v[120:123], v157 offset:512
	ds_read_b128 v[124:127], v157 offset:528
	v_cmp_eq_u32_e32 vcc, 7, v152
	s_waitcnt lgkmcnt(2)
	s_nop 0
	v_cndmask_b32_e64 v159, 0, 1.0, vcc
	v_fma_f32 v159, -v136, v104, v159
	v_fma_f32 v159, -v137, v105, v159
	v_fma_f32 v159, -v138, v106, v159
	v_fma_f32 v159, -v139, v107, v159
	v_fma_f32 v159, -v140, v108, v159
	v_fma_f32 v159, -v141, v109, v159
	v_fma_f32 v159, -v142, v110, v159
	v_mul_f32_e32 v111, v95, v159
	ds_read_b128 v[136:139], v157 offset:576
	ds_read_b128 v[140:143], v157 offset:592
	ds_read_b128 v[144:147], v157 offset:608
	v_cmp_eq_u32_e32 vcc, 8, v152
	s_waitcnt lgkmcnt(3)
	s_nop 0
	v_cndmask_b32_e64 v159, 0, 1.0, vcc
	v_fma_f32 v159, -v120, v104, v159
	v_fma_f32 v159, -v121, v105, v159
	v_fma_f32 v159, -v122, v106, v159
	v_fma_f32 v159, -v123, v107, v159
	v_fma_f32 v159, -v124, v108, v159
	v_fma_f32 v159, -v125, v109, v159
	v_fma_f32 v159, -v126, v110, v159
	v_fma_f32 v159, -v127, v111, v159
	v_mul_f32_e32 v112, v96, v159
	ds_read_b128 v[120:123], v157 offset:640
	ds_read_b128 v[124:127], v157 offset:656
	ds_read_b128 v[128:131], v157 offset:672
	v_cmp_eq_u32_e32 vcc, 9, v152
	s_waitcnt lgkmcnt(3)
	s_nop 0
	v_cndmask_b32_e64 v159, 0, 1.0, vcc
	v_fma_f32 v159, -v136, v104, v159
	v_fma_f32 v159, -v137, v105, v159
	v_fma_f32 v159, -v138, v106, v159
	v_fma_f32 v159, -v139, v107, v159
	v_fma_f32 v159, -v140, v108, v159
	v_fma_f32 v159, -v141, v109, v159
	v_fma_f32 v159, -v142, v110, v159
	v_fma_f32 v159, -v143, v111, v159
	v_fma_f32 v159, -v144, v112, v159
	v_mul_f32_e32 v113, v97, v159
	ds_read_b128 v[136:139], v157 offset:704
	ds_read_b128 v[140:143], v157 offset:720
	ds_read_b128 v[144:147], v157 offset:736
	v_cmp_eq_u32_e32 vcc, 10, v152
	s_waitcnt lgkmcnt(3)
; __device__ __forceinline__ void gdn_item(const Params& p, int item, float* sm) {
;     ...
;       for (int t = 0; t < TC; t++) {
;         const float4 k0 = *(const float4*)(bk + t * 128 + sub * 4);
;         const float4 k1 = *(const float4*)(bk + t * 128 + 64 + sub * 4);
;         const float4 q0 = *(const float4*)(bq + t * 128 + sub * 4);
;         const float4 q1 = *(const float4*)(bq + t * 128 + 64 + sub * 4);
;         const float v = bv[t * 16 + cw];
;         const float g = bg[t], be = bg[TC + t];
;         const float qk = bo[TC * 16 + t];
;         float pa = k0.x * S[0] + k0.y * S[1];
;         float pb2 = k0.z * S[2] + k0.w * S[3];
;         float qa = q0.x * S[0] + q0.y * S[1];
;         float qb2 = q0.z * S[2] + q0.w * S[3];
;         pa += k1.x * S[4] + k1.y * S[5];
;         pb2 += k1.z * S[6] + k1.w * S[7];
;         qa += q1.x * S[4] + q1.y * S[5];
;         qb2 += q1.z * S[6] + q1.w * S[7];
;         const float ks = dpp_sum16(pa + pb2);
;         const float qs = dpp_sum16(qa + qb2);
;         const float coef = be * (v - g * ks);
;         const float oo = g * qs + coef * qk;
;         S[0] = g * S[0] + coef * k0.x; S[1] = g * S[1] + coef * k0.y; S[2] = g * S[2] + coef * k0.z; S[3] = g * S[3] + coef * k0.w;
;         S[4] = g * S[4] + coef * k1.x; S[5] = g * S[5] + coef * k1.y; S[6] = g * S[6] + coef * k1.z; S[7] = g * S[7] + coef * k1.w;
;         oreg[t] = oo * 0.08838834764831845f;
	s_nop 0
	v_cndmask_b32_e64 v159, 0, 1.0, vcc
	v_fma_f32 v159, -v120, v104, v159
	v_fma_f32 v159, -v121, v105, v159
	v_fma_f32 v159, -v122, v106, v159
	v_fma_f32 v159, -v123, v107, v159
	v_fma_f32 v159, -v124, v108, v159
	v_fma_f32 v159, -v125, v109, v159
	v_fma_f32 v159, -v126, v110, v159
	v_fma_f32 v159, -v127, v111, v159
	v_fma_f32 v159, -v128, v112, v159
	v_fma_f32 v159, -v129, v113, v159
	v_mul_f32_e32 v114, v98, v159
	ds_read_b128 v[120:123], v157 offset:768
	ds_read_b128 v[124:127], v157 offset:784
	ds_read_b128 v[128:131], v157 offset:800
	v_cmp_eq_u32_e32 vcc, 11, v152
	s_waitcnt lgkmcnt(3)
	s_nop 0
	v_cndmask_b32_e64 v159, 0, 1.0, vcc
	v_fma_f32 v159, -v136, v104, v159
	v_fma_f32 v159, -v137, v105, v159
	v_fma_f32 v159, -v138, v106, v159
	v_fma_f32 v159, -v139, v107, v159
	v_fma_f32 v159, -v140, v108, v159
	v_fma_f32 v159, -v141, v109, v159
	v_fma_f32 v159, -v142, v110, v159
	v_fma_f32 v159, -v143, v111, v159
	v_fma_f32 v159, -v144, v112, v159
	v_fma_f32 v159, -v145, v113, v159
	v_fma_f32 v159, -v146, v114, v159
	v_mul_f32_e32 v115, v99, v159
	ds_read_b128 v[136:139], v157 offset:832
	ds_read_b128 v[140:143], v157 offset:848
	ds_read_b128 v[144:147], v157 offset:864
	ds_read_b128 v[148:151], v157 offset:880
	v_cmp_eq_u32_e32 vcc, 12, v152
	s_waitcnt lgkmcnt(4)
	s_nop 0
	v_cndmask_b32_e64 v159, 0, 1.0, vcc
	v_fma_f32 v159, -v120, v104, v159
	v_fma_f32 v159, -v121, v105, v159
	v_fma_f32 v159, -v122, v106, v159
	v_fma_f32 v159, -v123, v107, v159
	v_fma_f32 v159, -v124, v108, v159
	v_fma_f32 v159, -v125, v109, v159
	v_fma_f32 v159, -v126, v110, v159
	v_fma_f32 v159, -v127, v111, v159
	v_fma_f32 v159, -v128, v112, v159
	v_fma_f32 v159, -v129, v113, v159
	v_fma_f32 v159, -v130, v114, v159
	v_fma_f32 v159, -v131, v115, v159
	v_mul_f32_e32 v116, v100, v159
	ds_read_b128 v[120:123], v157 offset:896
	ds_read_b128 v[124:127], v157 offset:912
	ds_read_b128 v[128:131], v157 offset:928
	ds_read_b128 v[132:135], v157 offset:944
	v_cmp_eq_u32_e32 vcc, 13, v152
	s_waitcnt lgkmcnt(4)
	s_nop 0
	v_cndmask_b32_e64 v159, 0, 1.0, vcc
	v_fma_f32 v159, -v136, v104, v159
	v_fma_f32 v159, -v137, v105, v159
	v_fma_f32 v159, -v138, v106, v159
	v_fma_f32 v159, -v139, v107, v159
	v_fma_f32 v159, -v140, v108, v159
	v_fma_f32 v159, -v141, v109, v159
	v_fma_f32 v159, -v142, v110, v159
	v_fma_f32 v159, -v143, v111, v159
	v_fma_f32 v159, -v144, v112, v159
	v_fma_f32 v159, -v145, v113, v159
	v_fma_f32 v159, -v146, v114, v159
	v_fma_f32 v159, -v147, v115, v159
	v_fma_f32 v159, -v148, v116, v159
	v_mul_f32_e32 v117, v101, v159
	ds_read_b128 v[136:139], v157 offset:960
	ds_read_b128 v[140:143], v157 offset:976
	ds_read_b128 v[144:147], v157 offset:992
	ds_read_b128 v[148:151], v157 offset:1008
	v_cmp_eq_u32_e32 vcc, 14, v152
	s_waitcnt lgkmcnt(4)
	s_nop 0
	v_cndmask_b32_e64 v159, 0, 1.0, vcc
	v_fma_f32 v159, -v120, v104, v159
	v_fma_f32 v159, -v121, v105, v159
	v_fma_f32 v159, -v122, v106, v159
	v_fma_f32 v159, -v123, v107, v159
	v_fma_f32 v159, -v124, v108, v159
	v_fma_f32 v159, -v125, v109, v159
	v_fma_f32 v159, -v126, v110, v159
	v_fma_f32 v159, -v127, v111, v159
	v_fma_f32 v159, -v128, v112, v159
	v_fma_f32 v159, -v129, v113, v159
	v_fma_f32 v159, -v130, v114, v159
	v_fma_f32 v159, -v131, v115, v159
	v_fma_f32 v159, -v132, v116, v159
	v_fma_f32 v159, -v133, v117, v159
	v_mul_f32_e32 v118, v102, v159
	v_cmp_eq_u32_e32 vcc, 15, v152
	s_waitcnt lgkmcnt(0)
	s_nop 0
	v_cndmask_b32_e64 v159, 0, 1.0, vcc
	v_fma_f32 v159, -v136, v104, v159
	v_fma_f32 v159, -v137, v105, v159
	v_fma_f32 v159, -v138, v106, v159
	v_fma_f32 v159, -v139, v107, v159
	v_fma_f32 v159, -v140, v108, v159
	v_fma_f32 v159, -v141, v109, v159
	v_fma_f32 v159, -v142, v110, v159
	v_fma_f32 v159, -v143, v111, v159
	v_fma_f32 v159, -v144, v112, v159
	v_fma_f32 v159, -v145, v113, v159
	v_fma_f32 v159, -v146, v114, v159
	v_fma_f32 v159, -v147, v115, v159
	v_fma_f32 v159, -v148, v116, v159
	v_fma_f32 v159, -v149, v117, v159
	v_fma_f32 v159, -v150, v118, v159
	v_mul_f32_e32 v119, v103, v159
	v_lshl_add_u32 v158, v152, 2, v157
	ds_write_b32 v158, v104
	ds_write_b32 v158, v105 offset:64
	ds_write_b32 v158, v106 offset:128
	ds_write_b32 v158, v107 offset:192
	ds_write_b32 v158, v108 offset:256
	ds_write_b32 v158, v109 offset:320
	ds_write_b32 v158, v110 offset:384
	ds_write_b32 v158, v111 offset:448
	ds_write_b32 v158, v112 offset:512
	ds_write_b32 v158, v113 offset:576
	ds_write_b32 v158, v114 offset:640
	ds_write_b32 v158, v115 offset:704
	ds_write_b32 v158, v116 offset:768
	ds_write_b32 v158, v117 offset:832
	ds_write_b32 v158, v118 offset:896
	ds_write_b32 v158, v119 offset:960
	v_add_u32_e32 v156, s13, v155
	v_subrev_u32_e32 v156, s12, v156
	s_waitcnt lgkmcnt(0)
	ds_read_b128 v[120:123], v155
	s_waitcnt lgkmcnt(0)
	global_store_dwordx4 v156, v[120:123], s[8:9]
	s_add_i32 s2, s2, s11
	s_branch .Lmv_item
